# GEMM main loops: LDS-DMA loads use SGPR base + 32-bit VGPR offset (16 per-lane 64-bit address adds per K-step removed; two scalar sums added)
# speedup vs baseline: 1.0260x; 1.0069x over previous
.LBB0_178:
	s_add_u32 s26, s22, 0xfffc0080
	s_addc_u32 s27, s23, -1
	s_add_i32 s34, 0, 0x10000
	s_cmp_eq_u32 s59, 12
	s_cselect_b32 s31, s9, s27
	s_cselect_b32 s30, s15, s26
	s_cselect_b32 s27, s13, s58
	s_cselect_b32 s26, s56, s57
	s_add_i32 s35, 0, 0x14000
	v_add_u32_e32 v140, s34, v195
	v_add_u32_e32 v166, s35, v195
	ds_read_b128 v[128:131], v140
	ds_read_b128 v[132:135], v140 offset:1024
	ds_read_b128 v[136:139], v140 offset:2048
	ds_read_b128 v[140:143], v140 offset:3072
	ds_read_b128 v[144:147], v166
	ds_read_b128 v[148:151], v166 offset:1024
	ds_read_b128 v[180:183], v166 offset:2048
	ds_read_b128 v[184:187], v166 offset:3072
	s_add_i32 m0, s49, 0xc000
	ds_read_b128 v[188:191], v200
	ds_read_b128 v[202:205], v200 offset:1024
	ds_read_b128 v[206:209], v200 offset:2048
	ds_read_b128 v[210:213], v200 offset:3072
	ds_read_b128 v[228:231], v200 offset:4096
	ds_read_b128 v[232:235], v200 offset:5120
	ds_read_b128 v[236:239], v200 offset:6144
	ds_read_b128 v[240:243], v200 offset:7168
	global_load_lds_dwordx4 v160, s[22:23]
	s_add_i32 m0, s49, 0xe000
	s_nop 0
	global_load_lds_dwordx4 v162, s[22:23]
	s_waitcnt vmcnt(8)
	s_waitcnt lgkmcnt(0)
	s_barrier
	s_setprio 1
	s_waitcnt lgkmcnt(0)
	v_mfma_f32_16x16x32_bf16 v[124:127], v[128:131], v[188:191], v[124:127]
	v_mfma_f32_16x16x32_bf16 v[124:127], v[132:135], v[202:205], v[124:127]
	v_mfma_f32_16x16x32_bf16 v[120:123], v[136:139], v[188:191], v[120:123]
	v_mfma_f32_16x16x32_bf16 v[120:123], v[140:143], v[202:205], v[120:123]
	v_mfma_f32_16x16x32_bf16 v[112:115], v[128:131], v[206:209], v[112:115]
	v_mfma_f32_16x16x32_bf16 v[112:115], v[132:135], v[210:213], v[112:115]
	v_mfma_f32_16x16x32_bf16 v[104:107], v[136:139], v[206:209], v[104:107]
	v_mfma_f32_16x16x32_bf16 v[104:107], v[140:143], v[210:213], v[104:107]
	v_mfma_f32_16x16x32_bf16 v[96:99], v[128:131], v[228:231], v[96:99]
	v_mfma_f32_16x16x32_bf16 v[96:99], v[132:135], v[232:235], v[96:99]
	v_mfma_f32_16x16x32_bf16 v[88:91], v[136:139], v[228:231], v[88:91]
	v_mfma_f32_16x16x32_bf16 v[88:91], v[140:143], v[232:235], v[88:91]
	v_mfma_f32_16x16x32_bf16 v[80:83], v[128:131], v[236:239], v[80:83]
	v_mfma_f32_16x16x32_bf16 v[80:83], v[132:135], v[240:243], v[80:83]
	v_mfma_f32_16x16x32_bf16 v[72:75], v[136:139], v[236:239], v[72:75]
	v_mfma_f32_16x16x32_bf16 v[72:75], v[140:143], v[240:243], v[72:75]
	s_setprio 0
	s_setprio 1
	v_mfma_f32_16x16x32_bf16 v[116:119], v[144:147], v[188:191], v[116:119]
	v_mfma_f32_16x16x32_bf16 v[116:119], v[148:151], v[202:205], v[116:119]
	v_mfma_f32_16x16x32_bf16 v[108:111], v[180:183], v[188:191], v[108:111]
	v_mfma_f32_16x16x32_bf16 v[108:111], v[184:187], v[202:205], v[108:111]
	v_mfma_f32_16x16x32_bf16 v[100:103], v[144:147], v[206:209], v[100:103]
	v_mfma_f32_16x16x32_bf16 v[100:103], v[148:151], v[210:213], v[100:103]
	v_mfma_f32_16x16x32_bf16 v[92:95], v[180:183], v[206:209], v[92:95]
	v_mfma_f32_16x16x32_bf16 v[92:95], v[184:187], v[210:213], v[92:95]
	v_mfma_f32_16x16x32_bf16 v[84:87], v[144:147], v[228:231], v[84:87]
	v_mfma_f32_16x16x32_bf16 v[84:87], v[148:151], v[232:235], v[84:87]
	v_mfma_f32_16x16x32_bf16 v[76:79], v[180:183], v[228:231], v[76:79]
	v_mfma_f32_16x16x32_bf16 v[76:79], v[184:187], v[232:235], v[76:79]
	v_mfma_f32_16x16x32_bf16 v[68:71], v[144:147], v[236:239], v[68:71]
	v_mfma_f32_16x16x32_bf16 v[68:71], v[148:151], v[240:243], v[68:71]
	v_mfma_f32_16x16x32_bf16 v[64:67], v[180:183], v[236:239], v[64:67]
	v_mfma_f32_16x16x32_bf16 v[64:67], v[184:187], v[240:243], v[64:67]
	s_setprio 0
	s_barrier
	s_add_i32 s34, s34, s45
	s_add_u32 s98, s26, s20
	s_addc_u32 s99, s27, s21
	s_mov_b32 m0, s34
	ds_read_b128 v[188:191], v200 offset:16384
	ds_read_b128 v[202:205], v200 offset:17408
	ds_read_b128 v[206:209], v200 offset:18432
	ds_read_b128 v[210:213], v200 offset:19456
	ds_read_b128 v[228:231], v200 offset:20480
	ds_read_b128 v[232:235], v200 offset:21504
	ds_read_b128 v[236:239], v200 offset:22528
	ds_read_b128 v[240:243], v200 offset:23552
	global_load_lds_dwordx4 v168, s[26:27]
	s_add_i32 m0, s34, 0x2000
	s_add_u32 s36, s26, 0x40000
	s_addc_u32 s37, s27, 0
	s_add_i32 s34, s35, s45
	global_load_lds_dwordx4 v152, s[26:27]
	s_mov_b32 m0, s34
	s_nop 0
	global_load_lds_dwordx4 v168, s[36:37]
	s_add_i32 m0, s34, 0x2000
	s_nop 0
	global_load_lds_dwordx4 v152, s[36:37]
	s_add_u32 s100, s30, s20
	s_addc_u32 s101, s31, s21
	s_mov_b32 m0, s49
	s_nop 0
	global_load_lds_dwordx4 v156, s[30:31]
	s_mov_b32 m0, s50
	s_nop 0
	global_load_lds_dwordx4 v154, s[30:31]
	s_waitcnt vmcnt(8)
	s_waitcnt lgkmcnt(0)
	s_barrier
	s_setprio 1
	s_waitcnt lgkmcnt(0)
	v_mfma_f32_16x16x32_bf16 v[60:63], v[128:131], v[188:191], v[60:63]
	v_mfma_f32_16x16x32_bf16 v[60:63], v[132:135], v[202:205], v[60:63]
	v_mfma_f32_16x16x32_bf16 v[56:59], v[136:139], v[188:191], v[56:59]
	v_mfma_f32_16x16x32_bf16 v[56:59], v[140:143], v[202:205], v[56:59]
	v_mfma_f32_16x16x32_bf16 v[48:51], v[128:131], v[206:209], v[48:51]
	v_mfma_f32_16x16x32_bf16 v[48:51], v[132:135], v[210:213], v[48:51]
	v_mfma_f32_16x16x32_bf16 v[40:43], v[136:139], v[206:209], v[40:43]
	v_mfma_f32_16x16x32_bf16 v[40:43], v[140:143], v[210:213], v[40:43]
	v_mfma_f32_16x16x32_bf16 v[32:35], v[128:131], v[228:231], v[32:35]
	v_mfma_f32_16x16x32_bf16 v[32:35], v[132:135], v[232:235], v[32:35]
	v_mfma_f32_16x16x32_bf16 v[24:27], v[136:139], v[228:231], v[24:27]
	v_mfma_f32_16x16x32_bf16 v[24:27], v[140:143], v[232:235], v[24:27]
	v_mfma_f32_16x16x32_bf16 v[16:19], v[128:131], v[236:239], v[16:19]
	v_mfma_f32_16x16x32_bf16 v[16:19], v[132:135], v[240:243], v[16:19]
	v_mfma_f32_16x16x32_bf16 v[8:11], v[136:139], v[236:239], v[8:11]
	v_mfma_f32_16x16x32_bf16 v[8:11], v[140:143], v[240:243], v[8:11]
	s_setprio 0
	s_setprio 1
	v_mfma_f32_16x16x32_bf16 v[52:55], v[144:147], v[188:191], v[52:55]
	v_mfma_f32_16x16x32_bf16 v[52:55], v[148:151], v[202:205], v[52:55]
	v_mfma_f32_16x16x32_bf16 v[44:47], v[180:183], v[188:191], v[44:47]
	v_mfma_f32_16x16x32_bf16 v[44:47], v[184:187], v[202:205], v[44:47]
	v_mfma_f32_16x16x32_bf16 v[36:39], v[144:147], v[206:209], v[36:39]
	v_mfma_f32_16x16x32_bf16 v[36:39], v[148:151], v[210:213], v[36:39]
	v_mfma_f32_16x16x32_bf16 v[28:31], v[180:183], v[206:209], v[28:31]
	v_mfma_f32_16x16x32_bf16 v[28:31], v[184:187], v[210:213], v[28:31]
	v_mfma_f32_16x16x32_bf16 v[20:23], v[144:147], v[228:231], v[20:23]
	v_mfma_f32_16x16x32_bf16 v[20:23], v[148:151], v[232:235], v[20:23]
	v_mfma_f32_16x16x32_bf16 v[12:15], v[180:183], v[228:231], v[12:15]
	v_mfma_f32_16x16x32_bf16 v[12:15], v[184:187], v[232:235], v[12:15]
	v_mfma_f32_16x16x32_bf16 v[4:7], v[144:147], v[236:239], v[4:7]
	v_mfma_f32_16x16x32_bf16 v[4:7], v[148:151], v[240:243], v[4:7]
	v_mfma_f32_16x16x32_bf16 v[0:3], v[180:183], v[236:239], v[0:3]
	v_mfma_f32_16x16x32_bf16 v[0:3], v[184:187], v[240:243], v[0:3]
	s_setprio 0
	s_barrier
	s_add_i32 s34, 0, 0x18000
	s_add_i32 s35, 0, 0x1c000
	v_add_u32_e32 v140, s34, v195
	v_add_u32_e32 v184, s35, v195
	ds_read_b128 v[128:131], v140
	ds_read_b128 v[132:135], v140 offset:1024
	ds_read_b128 v[136:139], v140 offset:2048
	ds_read_b128 v[140:143], v140 offset:3072
	ds_read_b128 v[144:147], v184
	ds_read_b128 v[148:151], v184 offset:1024
	ds_read_b128 v[180:183], v184 offset:2048
	ds_read_b128 v[184:187], v184 offset:3072
	s_add_u32 s30, s30, 0x40000
	s_addc_u32 s31, s31, 0
	s_mov_b32 m0, s51
	ds_read_b128 v[188:191], v200 offset:32768
	ds_read_b128 v[202:205], v200 offset:33792
	ds_read_b128 v[206:209], v200 offset:34816
	ds_read_b128 v[210:213], v200 offset:35840
	ds_read_b128 v[228:231], v200 offset:36864
	ds_read_b128 v[232:235], v200 offset:37888
	ds_read_b128 v[236:239], v200 offset:38912
	ds_read_b128 v[240:243], v200 offset:39936
	global_load_lds_dwordx4 v156, s[30:31]
	s_mov_b32 m0, s52
	s_nop 0
	global_load_lds_dwordx4 v154, s[30:31]
	s_waitcnt vmcnt(8)
	s_waitcnt lgkmcnt(0)
	s_barrier
	s_setprio 1
	s_waitcnt lgkmcnt(0)
	v_mfma_f32_16x16x32_bf16 v[124:127], v[128:131], v[188:191], v[124:127]
	v_mfma_f32_16x16x32_bf16 v[124:127], v[132:135], v[202:205], v[124:127]
	v_mfma_f32_16x16x32_bf16 v[120:123], v[136:139], v[188:191], v[120:123]
	v_mfma_f32_16x16x32_bf16 v[120:123], v[140:143], v[202:205], v[120:123]
	v_mfma_f32_16x16x32_bf16 v[112:115], v[128:131], v[206:209], v[112:115]
	v_mfma_f32_16x16x32_bf16 v[112:115], v[132:135], v[210:213], v[112:115]
	v_mfma_f32_16x16x32_bf16 v[104:107], v[136:139], v[206:209], v[104:107]
	v_mfma_f32_16x16x32_bf16 v[104:107], v[140:143], v[210:213], v[104:107]
	v_mfma_f32_16x16x32_bf16 v[96:99], v[128:131], v[228:231], v[96:99]
	v_mfma_f32_16x16x32_bf16 v[96:99], v[132:135], v[232:235], v[96:99]
	v_mfma_f32_16x16x32_bf16 v[88:91], v[136:139], v[228:231], v[88:91]
	v_mfma_f32_16x16x32_bf16 v[88:91], v[140:143], v[232:235], v[88:91]
	v_mfma_f32_16x16x32_bf16 v[80:83], v[128:131], v[236:239], v[80:83]
	v_mfma_f32_16x16x32_bf16 v[80:83], v[132:135], v[240:243], v[80:83]
	v_mfma_f32_16x16x32_bf16 v[72:75], v[136:139], v[236:239], v[72:75]
	v_mfma_f32_16x16x32_bf16 v[72:75], v[140:143], v[240:243], v[72:75]
	s_setprio 0
	s_setprio 1
	v_mfma_f32_16x16x32_bf16 v[116:119], v[144:147], v[188:191], v[116:119]
	v_mfma_f32_16x16x32_bf16 v[116:119], v[148:151], v[202:205], v[116:119]
	v_mfma_f32_16x16x32_bf16 v[108:111], v[180:183], v[188:191], v[108:111]
	v_mfma_f32_16x16x32_bf16 v[108:111], v[184:187], v[202:205], v[108:111]
	v_mfma_f32_16x16x32_bf16 v[100:103], v[144:147], v[206:209], v[100:103]
	v_mfma_f32_16x16x32_bf16 v[100:103], v[148:151], v[210:213], v[100:103]
	v_mfma_f32_16x16x32_bf16 v[92:95], v[180:183], v[206:209], v[92:95]
	v_mfma_f32_16x16x32_bf16 v[92:95], v[184:187], v[210:213], v[92:95]
	v_mfma_f32_16x16x32_bf16 v[84:87], v[144:147], v[228:231], v[84:87]
	v_mfma_f32_16x16x32_bf16 v[84:87], v[148:151], v[232:235], v[84:87]
	v_mfma_f32_16x16x32_bf16 v[76:79], v[180:183], v[228:231], v[76:79]
	v_mfma_f32_16x16x32_bf16 v[76:79], v[184:187], v[232:235], v[76:79]
	v_mfma_f32_16x16x32_bf16 v[68:71], v[144:147], v[236:239], v[68:71]
	v_mfma_f32_16x16x32_bf16 v[68:71], v[148:151], v[240:243], v[68:71]
	v_mfma_f32_16x16x32_bf16 v[64:67], v[180:183], v[236:239], v[64:67]
	v_mfma_f32_16x16x32_bf16 v[64:67], v[184:187], v[240:243], v[64:67]
	s_setprio 0
	s_barrier
	s_add_i32 s30, s34, s45
	s_mov_b32 m0, s30
	ds_read_b128 v[188:191], v200 offset:49152
	ds_read_b128 v[202:205], v200 offset:50176
	ds_read_b128 v[206:209], v200 offset:51200
	ds_read_b128 v[210:213], v200 offset:52224
	ds_read_b128 v[228:231], v200 offset:53248
	ds_read_b128 v[232:235], v200 offset:54272
	ds_read_b128 v[236:239], v200 offset:55296
	ds_read_b128 v[240:243], v200 offset:56320
	global_load_lds_dwordx4 v168, s[98:99]
	s_add_i32 m0, s30, 0x2000
	s_add_u32 s26, s26, 0x40080
	s_addc_u32 s27, s27, 0
	s_add_i32 s30, s35, s45
	global_load_lds_dwordx4 v152, s[98:99]
	s_mov_b32 m0, s30
	s_nop 0
	global_load_lds_dwordx4 v168, s[26:27]
	s_add_i32 m0, s30, 0x2000
	s_nop 0
	global_load_lds_dwordx4 v152, s[26:27]
	s_mov_b32 m0, s24
	s_nop 0
	global_load_lds_dwordx4 v156, s[100:101]
	s_mov_b32 m0, s53
	s_nop 0
	global_load_lds_dwordx4 v154, s[100:101]
	s_waitcnt vmcnt(8)
	s_waitcnt lgkmcnt(0)
	s_barrier
	s_setprio 1
	s_waitcnt lgkmcnt(0)
	v_mfma_f32_16x16x32_bf16 v[60:63], v[128:131], v[188:191], v[60:63]
	v_mfma_f32_16x16x32_bf16 v[60:63], v[132:135], v[202:205], v[60:63]
	v_mfma_f32_16x16x32_bf16 v[56:59], v[136:139], v[188:191], v[56:59]
	v_mfma_f32_16x16x32_bf16 v[56:59], v[140:143], v[202:205], v[56:59]
	v_mfma_f32_16x16x32_bf16 v[48:51], v[128:131], v[206:209], v[48:51]
	v_mfma_f32_16x16x32_bf16 v[48:51], v[132:135], v[210:213], v[48:51]
	v_mfma_f32_16x16x32_bf16 v[40:43], v[136:139], v[206:209], v[40:43]
	v_mfma_f32_16x16x32_bf16 v[40:43], v[140:143], v[210:213], v[40:43]
	v_mfma_f32_16x16x32_bf16 v[32:35], v[128:131], v[228:231], v[32:35]
	v_mfma_f32_16x16x32_bf16 v[32:35], v[132:135], v[232:235], v[32:35]
	v_mfma_f32_16x16x32_bf16 v[24:27], v[136:139], v[228:231], v[24:27]
	v_mfma_f32_16x16x32_bf16 v[24:27], v[140:143], v[232:235], v[24:27]
	v_mfma_f32_16x16x32_bf16 v[16:19], v[128:131], v[236:239], v[16:19]
	v_mfma_f32_16x16x32_bf16 v[16:19], v[132:135], v[240:243], v[16:19]
	v_mfma_f32_16x16x32_bf16 v[8:11], v[136:139], v[236:239], v[8:11]
	v_mfma_f32_16x16x32_bf16 v[8:11], v[140:143], v[240:243], v[8:11]
	s_setprio 0
	s_setprio 1
	v_mfma_f32_16x16x32_bf16 v[52:55], v[144:147], v[188:191], v[52:55]
	v_mfma_f32_16x16x32_bf16 v[52:55], v[148:151], v[202:205], v[52:55]
	v_mfma_f32_16x16x32_bf16 v[44:47], v[180:183], v[188:191], v[44:47]
	v_mfma_f32_16x16x32_bf16 v[44:47], v[184:187], v[202:205], v[44:47]
	v_mfma_f32_16x16x32_bf16 v[36:39], v[144:147], v[206:209], v[36:39]
	v_mfma_f32_16x16x32_bf16 v[36:39], v[148:151], v[210:213], v[36:39]
	v_mfma_f32_16x16x32_bf16 v[28:31], v[180:183], v[206:209], v[28:31]
	v_mfma_f32_16x16x32_bf16 v[28:31], v[184:187], v[210:213], v[28:31]
	v_mfma_f32_16x16x32_bf16 v[20:23], v[144:147], v[228:231], v[20:23]
	v_mfma_f32_16x16x32_bf16 v[20:23], v[148:151], v[232:235], v[20:23]
	v_mfma_f32_16x16x32_bf16 v[12:15], v[180:183], v[228:231], v[12:15]
	v_mfma_f32_16x16x32_bf16 v[12:15], v[184:187], v[232:235], v[12:15]
	v_mfma_f32_16x16x32_bf16 v[4:7], v[144:147], v[236:239], v[4:7]
	v_mfma_f32_16x16x32_bf16 v[4:7], v[148:151], v[240:243], v[4:7]
	v_mfma_f32_16x16x32_bf16 v[0:3], v[180:183], v[236:239], v[0:3]
	v_mfma_f32_16x16x32_bf16 v[0:3], v[184:187], v[240:243], v[0:3]
	s_setprio 0
	s_barrier
	s_add_i32 s59, s59, 2
	s_add_u32 s22, s22, 0x100
	s_addc_u32 s23, s23, 0
	s_add_u32 s57, s57, 0x100
	s_addc_u32 s58, s58, 0
	s_cmp_gt_u32 s59, 13
	s_cbranch_scc0 .LBB0_178
	s_and_b64 vcc, exec, s[10:11]
	s_cbranch_vccz .LBB0_181
	s_barrier

.LBB0_776:
	s_add_u32 s26, s22, 0xfffc0080
	s_addc_u32 s27, s23, -1
	s_add_i32 s36, 0, 0x10000
	s_cmp_eq_u32 s55, 12
	s_cselect_b32 s31, s15, s27
	s_cselect_b32 s30, s51, s26
	s_cselect_b32 s27, s13, s54
	s_cselect_b32 s26, s52, s53
	s_add_i32 s56, 0, 0x14000
	v_add_u32_e32 v140, s36, v204
	v_add_u32_e32 v156, s56, v204
	ds_read_b128 v[128:131], v140
	ds_read_b128 v[132:135], v140 offset:1024
	ds_read_b128 v[136:139], v140 offset:2048
	ds_read_b128 v[140:143], v140 offset:3072
	ds_read_b128 v[144:147], v156
	ds_read_b128 v[148:151], v156 offset:1024
	ds_read_b128 v[152:155], v156 offset:2048
	ds_read_b128 v[156:159], v156 offset:3072
	s_add_i32 m0, s42, 0xc000
	ds_read_b128 v[182:185], v206
	ds_read_b128 v[186:189], v206 offset:1024
	ds_read_b128 v[190:193], v206 offset:2048
	ds_read_b128 v[194:197], v206 offset:3072
	ds_read_b128 v[198:201], v206 offset:4096
	ds_read_b128 v[208:211], v206 offset:5120
	ds_read_b128 v[212:215], v206 offset:6144
	ds_read_b128 v[228:231], v206 offset:7168
	global_load_lds_dwordx4 v166, s[22:23]
	s_add_i32 m0, s42, 0xe000
	s_nop 0
	global_load_lds_dwordx4 v180, s[22:23]
	s_waitcnt vmcnt(8)
	s_waitcnt lgkmcnt(0)
	s_barrier
	s_setprio 1
	s_waitcnt lgkmcnt(0)
	v_mfma_f32_16x16x32_bf16 v[124:127], v[128:131], v[182:185], v[124:127]
	v_mfma_f32_16x16x32_bf16 v[124:127], v[132:135], v[186:189], v[124:127]
	v_mfma_f32_16x16x32_bf16 v[120:123], v[136:139], v[182:185], v[120:123]
	v_mfma_f32_16x16x32_bf16 v[120:123], v[140:143], v[186:189], v[120:123]
	v_mfma_f32_16x16x32_bf16 v[108:111], v[128:131], v[190:193], v[108:111]
	v_mfma_f32_16x16x32_bf16 v[108:111], v[132:135], v[194:197], v[108:111]
	v_mfma_f32_16x16x32_bf16 v[104:107], v[136:139], v[190:193], v[104:107]
	v_mfma_f32_16x16x32_bf16 v[104:107], v[140:143], v[194:197], v[104:107]
	v_mfma_f32_16x16x32_bf16 v[92:95], v[128:131], v[198:201], v[92:95]
	v_mfma_f32_16x16x32_bf16 v[92:95], v[132:135], v[208:211], v[92:95]
	v_mfma_f32_16x16x32_bf16 v[88:91], v[136:139], v[198:201], v[88:91]
	v_mfma_f32_16x16x32_bf16 v[88:91], v[140:143], v[208:211], v[88:91]
	v_mfma_f32_16x16x32_bf16 v[76:79], v[128:131], v[212:215], v[76:79]
	v_mfma_f32_16x16x32_bf16 v[76:79], v[132:135], v[228:231], v[76:79]
	v_mfma_f32_16x16x32_bf16 v[72:75], v[136:139], v[212:215], v[72:75]
	v_mfma_f32_16x16x32_bf16 v[72:75], v[140:143], v[228:231], v[72:75]
	s_setprio 0
	s_setprio 1
	v_mfma_f32_16x16x32_bf16 v[116:119], v[144:147], v[182:185], v[116:119]
	v_mfma_f32_16x16x32_bf16 v[116:119], v[148:151], v[186:189], v[116:119]
	v_mfma_f32_16x16x32_bf16 v[112:115], v[152:155], v[182:185], v[112:115]
	v_mfma_f32_16x16x32_bf16 v[112:115], v[156:159], v[186:189], v[112:115]
	v_mfma_f32_16x16x32_bf16 v[100:103], v[144:147], v[190:193], v[100:103]
	v_mfma_f32_16x16x32_bf16 v[100:103], v[148:151], v[194:197], v[100:103]
	v_mfma_f32_16x16x32_bf16 v[96:99], v[152:155], v[190:193], v[96:99]
	v_mfma_f32_16x16x32_bf16 v[96:99], v[156:159], v[194:197], v[96:99]
	v_mfma_f32_16x16x32_bf16 v[84:87], v[144:147], v[198:201], v[84:87]
	v_mfma_f32_16x16x32_bf16 v[84:87], v[148:151], v[208:211], v[84:87]
	v_mfma_f32_16x16x32_bf16 v[80:83], v[152:155], v[198:201], v[80:83]
	v_mfma_f32_16x16x32_bf16 v[80:83], v[156:159], v[208:211], v[80:83]
	v_mfma_f32_16x16x32_bf16 v[68:71], v[144:147], v[212:215], v[68:71]
	v_mfma_f32_16x16x32_bf16 v[68:71], v[148:151], v[228:231], v[68:71]
	v_mfma_f32_16x16x32_bf16 v[64:67], v[152:155], v[212:215], v[64:67]
	v_mfma_f32_16x16x32_bf16 v[64:67], v[156:159], v[228:231], v[64:67]
	s_setprio 0
	s_barrier
	s_add_i32 s36, s36, s35
	s_add_u32 s98, s26, s20
	s_addc_u32 s99, s27, s21
	s_mov_b32 m0, s36
	ds_read_b128 v[182:185], v206 offset:16384
	ds_read_b128 v[186:189], v206 offset:17408
	ds_read_b128 v[190:193], v206 offset:18432
	ds_read_b128 v[194:197], v206 offset:19456
	ds_read_b128 v[198:201], v206 offset:20480
	ds_read_b128 v[208:211], v206 offset:21504
	ds_read_b128 v[212:215], v206 offset:22528
	ds_read_b128 v[228:231], v206 offset:23552
	global_load_lds_dwordx4 v168, s[26:27]
	s_add_i32 m0, s36, 0x2000
	s_add_u32 s36, s26, 0x40000
	s_addc_u32 s37, s27, 0
	s_add_i32 s56, s56, s35
	global_load_lds_dwordx4 v160, s[26:27]
	s_mov_b32 m0, s56
	s_nop 0
	global_load_lds_dwordx4 v168, s[36:37]
	s_add_i32 m0, s56, 0x2000
	s_nop 0
	global_load_lds_dwordx4 v160, s[36:37]
	s_add_u32 s100, s30, s20
	s_addc_u32 s101, s31, s21
	s_mov_b32 m0, s42
	s_nop 0
	global_load_lds_dwordx4 v164, s[30:31]
	s_mov_b32 m0, s43
	s_nop 0
	global_load_lds_dwordx4 v162, s[30:31]
	s_waitcnt vmcnt(8)
	s_waitcnt lgkmcnt(0)
	s_barrier
	s_setprio 1
	s_waitcnt lgkmcnt(0)
	v_mfma_f32_16x16x32_bf16 v[60:63], v[128:131], v[182:185], v[60:63]
	v_mfma_f32_16x16x32_bf16 v[60:63], v[132:135], v[186:189], v[60:63]
	v_mfma_f32_16x16x32_bf16 v[56:59], v[136:139], v[182:185], v[56:59]
	v_mfma_f32_16x16x32_bf16 v[56:59], v[140:143], v[186:189], v[56:59]
	v_mfma_f32_16x16x32_bf16 v[44:47], v[128:131], v[190:193], v[44:47]
	v_mfma_f32_16x16x32_bf16 v[44:47], v[132:135], v[194:197], v[44:47]
	v_mfma_f32_16x16x32_bf16 v[40:43], v[136:139], v[190:193], v[40:43]
	v_mfma_f32_16x16x32_bf16 v[40:43], v[140:143], v[194:197], v[40:43]
	v_mfma_f32_16x16x32_bf16 v[28:31], v[128:131], v[198:201], v[28:31]
	v_mfma_f32_16x16x32_bf16 v[28:31], v[132:135], v[208:211], v[28:31]
	v_mfma_f32_16x16x32_bf16 v[24:27], v[136:139], v[198:201], v[24:27]
	v_mfma_f32_16x16x32_bf16 v[24:27], v[140:143], v[208:211], v[24:27]
	v_mfma_f32_16x16x32_bf16 v[12:15], v[128:131], v[212:215], v[12:15]
	v_mfma_f32_16x16x32_bf16 v[12:15], v[132:135], v[228:231], v[12:15]
	v_mfma_f32_16x16x32_bf16 v[8:11], v[136:139], v[212:215], v[8:11]
	v_mfma_f32_16x16x32_bf16 v[8:11], v[140:143], v[228:231], v[8:11]
	s_setprio 0
	s_setprio 1
	v_mfma_f32_16x16x32_bf16 v[52:55], v[144:147], v[182:185], v[52:55]
	v_mfma_f32_16x16x32_bf16 v[52:55], v[148:151], v[186:189], v[52:55]
	v_mfma_f32_16x16x32_bf16 v[48:51], v[152:155], v[182:185], v[48:51]
	v_mfma_f32_16x16x32_bf16 v[48:51], v[156:159], v[186:189], v[48:51]
	v_mfma_f32_16x16x32_bf16 v[36:39], v[144:147], v[190:193], v[36:39]
	v_mfma_f32_16x16x32_bf16 v[36:39], v[148:151], v[194:197], v[36:39]
	v_mfma_f32_16x16x32_bf16 v[32:35], v[152:155], v[190:193], v[32:35]
	v_mfma_f32_16x16x32_bf16 v[32:35], v[156:159], v[194:197], v[32:35]
	v_mfma_f32_16x16x32_bf16 v[20:23], v[144:147], v[198:201], v[20:23]
	v_mfma_f32_16x16x32_bf16 v[20:23], v[148:151], v[208:211], v[20:23]
	v_mfma_f32_16x16x32_bf16 v[16:19], v[152:155], v[198:201], v[16:19]
	v_mfma_f32_16x16x32_bf16 v[16:19], v[156:159], v[208:211], v[16:19]
	v_mfma_f32_16x16x32_bf16 v[4:7], v[144:147], v[212:215], v[4:7]
	v_mfma_f32_16x16x32_bf16 v[4:7], v[148:151], v[228:231], v[4:7]
	v_mfma_f32_16x16x32_bf16 v[0:3], v[152:155], v[212:215], v[0:3]
	v_mfma_f32_16x16x32_bf16 v[0:3], v[156:159], v[228:231], v[0:3]
	s_setprio 0
	s_barrier
	s_add_i32 s36, 0, 0x18000
	s_add_i32 s37, 0, 0x1c000
	v_add_u32_e32 v140, s36, v204
	v_add_u32_e32 v156, s37, v204
	ds_read_b128 v[128:131], v140
	ds_read_b128 v[132:135], v140 offset:1024
	ds_read_b128 v[136:139], v140 offset:2048
	ds_read_b128 v[140:143], v140 offset:3072
	ds_read_b128 v[144:147], v156
	ds_read_b128 v[148:151], v156 offset:1024
	ds_read_b128 v[152:155], v156 offset:2048
	ds_read_b128 v[156:159], v156 offset:3072
	s_add_u32 s30, s30, 0x40000
	s_addc_u32 s31, s31, 0
	s_mov_b32 m0, s44
	ds_read_b128 v[182:185], v206 offset:32768
	ds_read_b128 v[186:189], v206 offset:33792
	ds_read_b128 v[190:193], v206 offset:34816
	ds_read_b128 v[194:197], v206 offset:35840
	ds_read_b128 v[198:201], v206 offset:36864
	ds_read_b128 v[208:211], v206 offset:37888
	ds_read_b128 v[212:215], v206 offset:38912
	ds_read_b128 v[228:231], v206 offset:39936
	global_load_lds_dwordx4 v164, s[30:31]
	s_mov_b32 m0, s45
	s_nop 0
	global_load_lds_dwordx4 v162, s[30:31]
	s_waitcnt vmcnt(8)
	s_waitcnt lgkmcnt(0)
	s_barrier
	s_setprio 1
	s_waitcnt lgkmcnt(0)
	v_mfma_f32_16x16x32_bf16 v[124:127], v[128:131], v[182:185], v[124:127]
	v_mfma_f32_16x16x32_bf16 v[124:127], v[132:135], v[186:189], v[124:127]
	v_mfma_f32_16x16x32_bf16 v[120:123], v[136:139], v[182:185], v[120:123]
	v_mfma_f32_16x16x32_bf16 v[120:123], v[140:143], v[186:189], v[120:123]
	v_mfma_f32_16x16x32_bf16 v[108:111], v[128:131], v[190:193], v[108:111]
	v_mfma_f32_16x16x32_bf16 v[108:111], v[132:135], v[194:197], v[108:111]
	v_mfma_f32_16x16x32_bf16 v[104:107], v[136:139], v[190:193], v[104:107]
	v_mfma_f32_16x16x32_bf16 v[104:107], v[140:143], v[194:197], v[104:107]
	v_mfma_f32_16x16x32_bf16 v[92:95], v[128:131], v[198:201], v[92:95]
	v_mfma_f32_16x16x32_bf16 v[92:95], v[132:135], v[208:211], v[92:95]
	v_mfma_f32_16x16x32_bf16 v[88:91], v[136:139], v[198:201], v[88:91]
	v_mfma_f32_16x16x32_bf16 v[88:91], v[140:143], v[208:211], v[88:91]
	v_mfma_f32_16x16x32_bf16 v[76:79], v[128:131], v[212:215], v[76:79]
	v_mfma_f32_16x16x32_bf16 v[76:79], v[132:135], v[228:231], v[76:79]
	v_mfma_f32_16x16x32_bf16 v[72:75], v[136:139], v[212:215], v[72:75]
	v_mfma_f32_16x16x32_bf16 v[72:75], v[140:143], v[228:231], v[72:75]
	s_setprio 0
	s_setprio 1
	v_mfma_f32_16x16x32_bf16 v[116:119], v[144:147], v[182:185], v[116:119]
	v_mfma_f32_16x16x32_bf16 v[116:119], v[148:151], v[186:189], v[116:119]
	v_mfma_f32_16x16x32_bf16 v[112:115], v[152:155], v[182:185], v[112:115]
	v_mfma_f32_16x16x32_bf16 v[112:115], v[156:159], v[186:189], v[112:115]
	v_mfma_f32_16x16x32_bf16 v[100:103], v[144:147], v[190:193], v[100:103]
	v_mfma_f32_16x16x32_bf16 v[100:103], v[148:151], v[194:197], v[100:103]
	v_mfma_f32_16x16x32_bf16 v[96:99], v[152:155], v[190:193], v[96:99]
	v_mfma_f32_16x16x32_bf16 v[96:99], v[156:159], v[194:197], v[96:99]
	v_mfma_f32_16x16x32_bf16 v[84:87], v[144:147], v[198:201], v[84:87]
	v_mfma_f32_16x16x32_bf16 v[84:87], v[148:151], v[208:211], v[84:87]
	v_mfma_f32_16x16x32_bf16 v[80:83], v[152:155], v[198:201], v[80:83]
	v_mfma_f32_16x16x32_bf16 v[80:83], v[156:159], v[208:211], v[80:83]
	v_mfma_f32_16x16x32_bf16 v[68:71], v[144:147], v[212:215], v[68:71]
	v_mfma_f32_16x16x32_bf16 v[68:71], v[148:151], v[228:231], v[68:71]
	v_mfma_f32_16x16x32_bf16 v[64:67], v[152:155], v[212:215], v[64:67]
	v_mfma_f32_16x16x32_bf16 v[64:67], v[156:159], v[228:231], v[64:67]
	s_setprio 0
	s_barrier
	s_add_i32 s30, s36, s35
	s_mov_b32 m0, s30
	ds_read_b128 v[182:185], v206 offset:49152
	ds_read_b128 v[186:189], v206 offset:50176
	ds_read_b128 v[190:193], v206 offset:51200
	ds_read_b128 v[194:197], v206 offset:52224
	ds_read_b128 v[198:201], v206 offset:53248
	ds_read_b128 v[208:211], v206 offset:54272
	ds_read_b128 v[212:215], v206 offset:55296
	ds_read_b128 v[228:231], v206 offset:56320
	global_load_lds_dwordx4 v168, s[98:99]
	s_add_i32 m0, s30, 0x2000
	s_add_u32 s26, s26, 0x40080
	s_addc_u32 s27, s27, 0
	s_add_i32 s30, s37, s35
	global_load_lds_dwordx4 v160, s[98:99]
	s_mov_b32 m0, s30
	s_nop 0
	global_load_lds_dwordx4 v168, s[26:27]
	s_add_i32 m0, s30, 0x2000
	s_nop 0
	global_load_lds_dwordx4 v160, s[26:27]
	s_mov_b32 m0, s47
	s_nop 0
	global_load_lds_dwordx4 v164, s[100:101]
	s_mov_b32 m0, s48
	s_nop 0
	global_load_lds_dwordx4 v162, s[100:101]
	s_waitcnt vmcnt(8)
	s_waitcnt lgkmcnt(0)
	s_barrier
	s_setprio 1
	s_waitcnt lgkmcnt(0)
	v_mfma_f32_16x16x32_bf16 v[60:63], v[128:131], v[182:185], v[60:63]
	v_mfma_f32_16x16x32_bf16 v[60:63], v[132:135], v[186:189], v[60:63]
	v_mfma_f32_16x16x32_bf16 v[56:59], v[136:139], v[182:185], v[56:59]
	v_mfma_f32_16x16x32_bf16 v[56:59], v[140:143], v[186:189], v[56:59]
	v_mfma_f32_16x16x32_bf16 v[44:47], v[128:131], v[190:193], v[44:47]
	v_mfma_f32_16x16x32_bf16 v[44:47], v[132:135], v[194:197], v[44:47]
	v_mfma_f32_16x16x32_bf16 v[40:43], v[136:139], v[190:193], v[40:43]
	v_mfma_f32_16x16x32_bf16 v[40:43], v[140:143], v[194:197], v[40:43]
	v_mfma_f32_16x16x32_bf16 v[28:31], v[128:131], v[198:201], v[28:31]
	v_mfma_f32_16x16x32_bf16 v[28:31], v[132:135], v[208:211], v[28:31]
	v_mfma_f32_16x16x32_bf16 v[24:27], v[136:139], v[198:201], v[24:27]
	v_mfma_f32_16x16x32_bf16 v[24:27], v[140:143], v[208:211], v[24:27]
	v_mfma_f32_16x16x32_bf16 v[12:15], v[128:131], v[212:215], v[12:15]
	v_mfma_f32_16x16x32_bf16 v[12:15], v[132:135], v[228:231], v[12:15]
	v_mfma_f32_16x16x32_bf16 v[8:11], v[136:139], v[212:215], v[8:11]
	v_mfma_f32_16x16x32_bf16 v[8:11], v[140:143], v[228:231], v[8:11]
	s_setprio 0
	s_setprio 1
	v_mfma_f32_16x16x32_bf16 v[52:55], v[144:147], v[182:185], v[52:55]
	v_mfma_f32_16x16x32_bf16 v[52:55], v[148:151], v[186:189], v[52:55]
	v_mfma_f32_16x16x32_bf16 v[48:51], v[152:155], v[182:185], v[48:51]
	v_mfma_f32_16x16x32_bf16 v[48:51], v[156:159], v[186:189], v[48:51]
	v_mfma_f32_16x16x32_bf16 v[36:39], v[144:147], v[190:193], v[36:39]
	v_mfma_f32_16x16x32_bf16 v[36:39], v[148:151], v[194:197], v[36:39]
	v_mfma_f32_16x16x32_bf16 v[32:35], v[152:155], v[190:193], v[32:35]
	v_mfma_f32_16x16x32_bf16 v[32:35], v[156:159], v[194:197], v[32:35]
	v_mfma_f32_16x16x32_bf16 v[20:23], v[144:147], v[198:201], v[20:23]
	v_mfma_f32_16x16x32_bf16 v[20:23], v[148:151], v[208:211], v[20:23]
	v_mfma_f32_16x16x32_bf16 v[16:19], v[152:155], v[198:201], v[16:19]
	v_mfma_f32_16x16x32_bf16 v[16:19], v[156:159], v[208:211], v[16:19]
	v_mfma_f32_16x16x32_bf16 v[4:7], v[144:147], v[212:215], v[4:7]
	v_mfma_f32_16x16x32_bf16 v[4:7], v[148:151], v[228:231], v[4:7]
	v_mfma_f32_16x16x32_bf16 v[0:3], v[152:155], v[212:215], v[0:3]
	v_mfma_f32_16x16x32_bf16 v[0:3], v[156:159], v[228:231], v[0:3]
	s_setprio 0
	s_barrier
	s_add_i32 s55, s55, 2
	s_add_u32 s22, s22, 0x100
	s_addc_u32 s23, s23, 0
	s_add_u32 s53, s53, 0x100
	s_addc_u32 s54, s54, 0
	s_cmp_gt_u32 s55, 13
	s_cbranch_scc0 .LBB0_776
	s_and_b64 vcc, exec, s[10:11]
	s_cbranch_vccz .LBB0_779
	s_barrier

.LBB0_890:
	s_add_u32 s18, s0, 0xfffc0080
	s_addc_u32 s19, s1, -1
	s_add_i32 s36, 0, 0x10000
	s_cmp_eq_u32 s50, 12
	s_cselect_b32 s23, s13, s19
	s_cselect_b32 s22, s46, s18
	s_cselect_b32 s19, s11, s49
	s_cselect_b32 s18, s47, s48
	s_add_i32 s51, 0, 0x14000
	v_add_u32_e32 v140, s36, v193
	v_add_u32_e32 v180, s51, v193
	ds_read_b128 v[128:131], v140
	ds_read_b128 v[132:135], v140 offset:1024
	ds_read_b128 v[136:139], v140 offset:2048
	ds_read_b128 v[140:143], v140 offset:3072
	ds_read_b128 v[144:147], v180
	ds_read_b128 v[148:151], v180 offset:1024
	ds_read_b128 v[164:167], v180 offset:2048
	ds_read_b128 v[180:183], v180 offset:3072
	s_add_i32 m0, s30, 0xc000
	ds_read_b128 v[184:187], v198
	ds_read_b128 v[188:191], v198 offset:1024
	ds_read_b128 v[200:203], v198 offset:2048
	ds_read_b128 v[204:207], v198 offset:3072
	ds_read_b128 v[208:211], v198 offset:4096
	ds_read_b128 v[212:215], v198 offset:5120
	ds_read_b128 v[228:231], v198 offset:6144
	ds_read_b128 v[232:235], v198 offset:7168
	global_load_lds_dwordx4 v160, s[0:1]
	s_add_i32 m0, s30, 0xe000
	s_nop 0
	global_load_lds_dwordx4 v162, s[0:1]
	s_waitcnt vmcnt(8)
	s_waitcnt lgkmcnt(0)
	s_barrier
	s_setprio 1
	s_waitcnt lgkmcnt(0)
	v_mfma_f32_16x16x32_bf16 v[124:127], v[128:131], v[184:187], v[124:127]
	v_mfma_f32_16x16x32_bf16 v[124:127], v[132:135], v[188:191], v[124:127]
	v_mfma_f32_16x16x32_bf16 v[120:123], v[136:139], v[184:187], v[120:123]
	v_mfma_f32_16x16x32_bf16 v[120:123], v[140:143], v[188:191], v[120:123]
	v_mfma_f32_16x16x32_bf16 v[108:111], v[128:131], v[200:203], v[108:111]
	v_mfma_f32_16x16x32_bf16 v[108:111], v[132:135], v[204:207], v[108:111]
	v_mfma_f32_16x16x32_bf16 v[104:107], v[136:139], v[200:203], v[104:107]
	v_mfma_f32_16x16x32_bf16 v[104:107], v[140:143], v[204:207], v[104:107]
	v_mfma_f32_16x16x32_bf16 v[92:95], v[128:131], v[208:211], v[92:95]
	v_mfma_f32_16x16x32_bf16 v[92:95], v[132:135], v[212:215], v[92:95]
	v_mfma_f32_16x16x32_bf16 v[88:91], v[136:139], v[208:211], v[88:91]
	v_mfma_f32_16x16x32_bf16 v[88:91], v[140:143], v[212:215], v[88:91]
	v_mfma_f32_16x16x32_bf16 v[76:79], v[128:131], v[228:231], v[76:79]
	v_mfma_f32_16x16x32_bf16 v[76:79], v[132:135], v[232:235], v[76:79]
	v_mfma_f32_16x16x32_bf16 v[72:75], v[136:139], v[228:231], v[72:75]
	v_mfma_f32_16x16x32_bf16 v[72:75], v[140:143], v[232:235], v[72:75]
	s_setprio 0
	s_setprio 1
	v_mfma_f32_16x16x32_bf16 v[116:119], v[144:147], v[184:187], v[116:119]
	v_mfma_f32_16x16x32_bf16 v[116:119], v[148:151], v[188:191], v[116:119]
	v_mfma_f32_16x16x32_bf16 v[112:115], v[164:167], v[184:187], v[112:115]
	v_mfma_f32_16x16x32_bf16 v[112:115], v[180:183], v[188:191], v[112:115]
	v_mfma_f32_16x16x32_bf16 v[100:103], v[144:147], v[200:203], v[100:103]
	v_mfma_f32_16x16x32_bf16 v[100:103], v[148:151], v[204:207], v[100:103]
	v_mfma_f32_16x16x32_bf16 v[96:99], v[164:167], v[200:203], v[96:99]
	v_mfma_f32_16x16x32_bf16 v[96:99], v[180:183], v[204:207], v[96:99]
	v_mfma_f32_16x16x32_bf16 v[84:87], v[144:147], v[208:211], v[84:87]
	v_mfma_f32_16x16x32_bf16 v[84:87], v[148:151], v[212:215], v[84:87]
	v_mfma_f32_16x16x32_bf16 v[80:83], v[164:167], v[208:211], v[80:83]
	v_mfma_f32_16x16x32_bf16 v[80:83], v[180:183], v[212:215], v[80:83]
	v_mfma_f32_16x16x32_bf16 v[68:71], v[144:147], v[228:231], v[68:71]
	v_mfma_f32_16x16x32_bf16 v[68:71], v[148:151], v[232:235], v[68:71]
	v_mfma_f32_16x16x32_bf16 v[64:67], v[164:167], v[228:231], v[64:67]
	v_mfma_f32_16x16x32_bf16 v[64:67], v[180:183], v[232:235], v[64:67]
	s_setprio 0
	s_barrier
	s_add_i32 s36, s36, s27
	s_add_u32 s98, s18, s20
	s_addc_u32 s99, s19, s21
	s_mov_b32 m0, s36
	ds_read_b128 v[184:187], v198 offset:16384
	ds_read_b128 v[188:191], v198 offset:17408
	ds_read_b128 v[200:203], v198 offset:18432
	ds_read_b128 v[204:207], v198 offset:19456
	ds_read_b128 v[208:211], v198 offset:20480
	ds_read_b128 v[212:215], v198 offset:21504
	ds_read_b128 v[228:231], v198 offset:22528
	ds_read_b128 v[232:235], v198 offset:23552
	global_load_lds_dwordx4 v168, s[18:19]
	s_add_i32 m0, s36, 0x2000
	s_add_u32 s36, s18, 0x40000
	s_addc_u32 s37, s19, 0
	s_add_i32 s51, s51, s27
	global_load_lds_dwordx4 v152, s[18:19]
	s_mov_b32 m0, s51
	s_nop 0
	global_load_lds_dwordx4 v168, s[36:37]
	s_add_i32 m0, s51, 0x2000
	s_nop 0
	global_load_lds_dwordx4 v152, s[36:37]
	s_add_u32 s100, s22, s20
	s_addc_u32 s101, s23, s21
	s_mov_b32 m0, s30
	s_nop 0
	global_load_lds_dwordx4 v156, s[22:23]
	s_mov_b32 m0, s31
	s_nop 0
	global_load_lds_dwordx4 v154, s[22:23]
	s_waitcnt vmcnt(8)
	s_waitcnt lgkmcnt(0)
	s_barrier
	s_setprio 1
	s_waitcnt lgkmcnt(0)
	v_mfma_f32_16x16x32_bf16 v[60:63], v[128:131], v[184:187], v[60:63]
	v_mfma_f32_16x16x32_bf16 v[60:63], v[132:135], v[188:191], v[60:63]
	v_mfma_f32_16x16x32_bf16 v[56:59], v[136:139], v[184:187], v[56:59]
	v_mfma_f32_16x16x32_bf16 v[56:59], v[140:143], v[188:191], v[56:59]
	v_mfma_f32_16x16x32_bf16 v[44:47], v[128:131], v[200:203], v[44:47]
	v_mfma_f32_16x16x32_bf16 v[44:47], v[132:135], v[204:207], v[44:47]
	v_mfma_f32_16x16x32_bf16 v[40:43], v[136:139], v[200:203], v[40:43]
	v_mfma_f32_16x16x32_bf16 v[40:43], v[140:143], v[204:207], v[40:43]
	v_mfma_f32_16x16x32_bf16 v[28:31], v[128:131], v[208:211], v[28:31]
	v_mfma_f32_16x16x32_bf16 v[28:31], v[132:135], v[212:215], v[28:31]
	v_mfma_f32_16x16x32_bf16 v[24:27], v[136:139], v[208:211], v[24:27]
	v_mfma_f32_16x16x32_bf16 v[24:27], v[140:143], v[212:215], v[24:27]
	v_mfma_f32_16x16x32_bf16 v[12:15], v[128:131], v[228:231], v[12:15]
	v_mfma_f32_16x16x32_bf16 v[12:15], v[132:135], v[232:235], v[12:15]
	v_mfma_f32_16x16x32_bf16 v[8:11], v[136:139], v[228:231], v[8:11]
	v_mfma_f32_16x16x32_bf16 v[8:11], v[140:143], v[232:235], v[8:11]
	s_setprio 0
	s_setprio 1
	v_mfma_f32_16x16x32_bf16 v[52:55], v[144:147], v[184:187], v[52:55]
	v_mfma_f32_16x16x32_bf16 v[52:55], v[148:151], v[188:191], v[52:55]
	v_mfma_f32_16x16x32_bf16 v[48:51], v[164:167], v[184:187], v[48:51]
	v_mfma_f32_16x16x32_bf16 v[48:51], v[180:183], v[188:191], v[48:51]
	v_mfma_f32_16x16x32_bf16 v[36:39], v[144:147], v[200:203], v[36:39]
	v_mfma_f32_16x16x32_bf16 v[36:39], v[148:151], v[204:207], v[36:39]
	v_mfma_f32_16x16x32_bf16 v[32:35], v[164:167], v[200:203], v[32:35]
	v_mfma_f32_16x16x32_bf16 v[32:35], v[180:183], v[204:207], v[32:35]
	v_mfma_f32_16x16x32_bf16 v[20:23], v[144:147], v[208:211], v[20:23]
	v_mfma_f32_16x16x32_bf16 v[20:23], v[148:151], v[212:215], v[20:23]
	v_mfma_f32_16x16x32_bf16 v[16:19], v[164:167], v[208:211], v[16:19]
	v_mfma_f32_16x16x32_bf16 v[16:19], v[180:183], v[212:215], v[16:19]
	v_mfma_f32_16x16x32_bf16 v[4:7], v[144:147], v[228:231], v[4:7]
	v_mfma_f32_16x16x32_bf16 v[4:7], v[148:151], v[232:235], v[4:7]
	v_mfma_f32_16x16x32_bf16 v[0:3], v[164:167], v[228:231], v[0:3]
	v_mfma_f32_16x16x32_bf16 v[0:3], v[180:183], v[232:235], v[0:3]
	s_setprio 0
	s_barrier
	s_add_i32 s36, 0, 0x18000
	s_add_i32 s37, 0, 0x1c000
	v_add_u32_e32 v140, s36, v193
	v_add_u32_e32 v180, s37, v193
	ds_read_b128 v[128:131], v140
	ds_read_b128 v[132:135], v140 offset:1024
	ds_read_b128 v[136:139], v140 offset:2048
	ds_read_b128 v[140:143], v140 offset:3072
	ds_read_b128 v[144:147], v180
	ds_read_b128 v[148:151], v180 offset:1024
	ds_read_b128 v[164:167], v180 offset:2048
	ds_read_b128 v[180:183], v180 offset:3072
	s_add_u32 s22, s22, 0x40000
	s_addc_u32 s23, s23, 0
	s_mov_b32 m0, s34
	ds_read_b128 v[184:187], v198 offset:32768
	ds_read_b128 v[188:191], v198 offset:33792
	ds_read_b128 v[200:203], v198 offset:34816
	ds_read_b128 v[204:207], v198 offset:35840
	ds_read_b128 v[208:211], v198 offset:36864
	ds_read_b128 v[212:215], v198 offset:37888
	ds_read_b128 v[228:231], v198 offset:38912
	ds_read_b128 v[232:235], v198 offset:39936
	global_load_lds_dwordx4 v156, s[22:23]
	s_mov_b32 m0, s35
	s_nop 0
	global_load_lds_dwordx4 v154, s[22:23]
	s_waitcnt vmcnt(8)
	s_waitcnt lgkmcnt(0)
	s_barrier
	s_setprio 1
	s_waitcnt lgkmcnt(0)
	v_mfma_f32_16x16x32_bf16 v[124:127], v[128:131], v[184:187], v[124:127]
	v_mfma_f32_16x16x32_bf16 v[124:127], v[132:135], v[188:191], v[124:127]
	v_mfma_f32_16x16x32_bf16 v[120:123], v[136:139], v[184:187], v[120:123]
	v_mfma_f32_16x16x32_bf16 v[120:123], v[140:143], v[188:191], v[120:123]
	v_mfma_f32_16x16x32_bf16 v[108:111], v[128:131], v[200:203], v[108:111]
	v_mfma_f32_16x16x32_bf16 v[108:111], v[132:135], v[204:207], v[108:111]
	v_mfma_f32_16x16x32_bf16 v[104:107], v[136:139], v[200:203], v[104:107]
	v_mfma_f32_16x16x32_bf16 v[104:107], v[140:143], v[204:207], v[104:107]
	v_mfma_f32_16x16x32_bf16 v[92:95], v[128:131], v[208:211], v[92:95]
	v_mfma_f32_16x16x32_bf16 v[92:95], v[132:135], v[212:215], v[92:95]
	v_mfma_f32_16x16x32_bf16 v[88:91], v[136:139], v[208:211], v[88:91]
	v_mfma_f32_16x16x32_bf16 v[88:91], v[140:143], v[212:215], v[88:91]
	v_mfma_f32_16x16x32_bf16 v[76:79], v[128:131], v[228:231], v[76:79]
	v_mfma_f32_16x16x32_bf16 v[76:79], v[132:135], v[232:235], v[76:79]
	v_mfma_f32_16x16x32_bf16 v[72:75], v[136:139], v[228:231], v[72:75]
	v_mfma_f32_16x16x32_bf16 v[72:75], v[140:143], v[232:235], v[72:75]
	s_setprio 0
	s_setprio 1
	v_mfma_f32_16x16x32_bf16 v[116:119], v[144:147], v[184:187], v[116:119]
	v_mfma_f32_16x16x32_bf16 v[116:119], v[148:151], v[188:191], v[116:119]
	v_mfma_f32_16x16x32_bf16 v[112:115], v[164:167], v[184:187], v[112:115]
	v_mfma_f32_16x16x32_bf16 v[112:115], v[180:183], v[188:191], v[112:115]
	v_mfma_f32_16x16x32_bf16 v[100:103], v[144:147], v[200:203], v[100:103]
	v_mfma_f32_16x16x32_bf16 v[100:103], v[148:151], v[204:207], v[100:103]
	v_mfma_f32_16x16x32_bf16 v[96:99], v[164:167], v[200:203], v[96:99]
	v_mfma_f32_16x16x32_bf16 v[96:99], v[180:183], v[204:207], v[96:99]
	v_mfma_f32_16x16x32_bf16 v[84:87], v[144:147], v[208:211], v[84:87]
	v_mfma_f32_16x16x32_bf16 v[84:87], v[148:151], v[212:215], v[84:87]
	v_mfma_f32_16x16x32_bf16 v[80:83], v[164:167], v[208:211], v[80:83]
	v_mfma_f32_16x16x32_bf16 v[80:83], v[180:183], v[212:215], v[80:83]
	v_mfma_f32_16x16x32_bf16 v[68:71], v[144:147], v[228:231], v[68:71]
	v_mfma_f32_16x16x32_bf16 v[68:71], v[148:151], v[232:235], v[68:71]
	v_mfma_f32_16x16x32_bf16 v[64:67], v[164:167], v[228:231], v[64:67]
	v_mfma_f32_16x16x32_bf16 v[64:67], v[180:183], v[232:235], v[64:67]
	s_setprio 0
	s_barrier
	s_add_i32 s22, s36, s27
	s_mov_b32 m0, s22
	ds_read_b128 v[184:187], v198 offset:49152
	ds_read_b128 v[188:191], v198 offset:50176
	ds_read_b128 v[200:203], v198 offset:51200
	ds_read_b128 v[204:207], v198 offset:52224
	ds_read_b128 v[208:211], v198 offset:53248
	ds_read_b128 v[212:215], v198 offset:54272
	ds_read_b128 v[228:231], v198 offset:55296
	ds_read_b128 v[232:235], v198 offset:56320
	global_load_lds_dwordx4 v168, s[98:99]
	s_add_i32 m0, s22, 0x2000
	s_add_u32 s18, s18, 0x40080
	s_addc_u32 s19, s19, 0
	s_add_i32 s22, s37, s27
	global_load_lds_dwordx4 v152, s[98:99]
	s_mov_b32 m0, s22
	s_nop 0
	global_load_lds_dwordx4 v168, s[18:19]
	s_add_i32 m0, s22, 0x2000
	s_nop 0
	global_load_lds_dwordx4 v152, s[18:19]
	s_mov_b32 m0, s24
	s_nop 0
	global_load_lds_dwordx4 v156, s[100:101]
	s_mov_b32 m0, s42
	s_nop 0
	global_load_lds_dwordx4 v154, s[100:101]
	s_waitcnt vmcnt(8)
	s_waitcnt lgkmcnt(0)
	s_barrier
	s_setprio 1
	s_waitcnt lgkmcnt(0)
	v_mfma_f32_16x16x32_bf16 v[60:63], v[128:131], v[184:187], v[60:63]
	v_mfma_f32_16x16x32_bf16 v[60:63], v[132:135], v[188:191], v[60:63]
	v_mfma_f32_16x16x32_bf16 v[56:59], v[136:139], v[184:187], v[56:59]
	v_mfma_f32_16x16x32_bf16 v[56:59], v[140:143], v[188:191], v[56:59]
	v_mfma_f32_16x16x32_bf16 v[44:47], v[128:131], v[200:203], v[44:47]
	v_mfma_f32_16x16x32_bf16 v[44:47], v[132:135], v[204:207], v[44:47]
	v_mfma_f32_16x16x32_bf16 v[40:43], v[136:139], v[200:203], v[40:43]
	v_mfma_f32_16x16x32_bf16 v[40:43], v[140:143], v[204:207], v[40:43]
	v_mfma_f32_16x16x32_bf16 v[28:31], v[128:131], v[208:211], v[28:31]
	v_mfma_f32_16x16x32_bf16 v[28:31], v[132:135], v[212:215], v[28:31]
	v_mfma_f32_16x16x32_bf16 v[24:27], v[136:139], v[208:211], v[24:27]
	v_mfma_f32_16x16x32_bf16 v[24:27], v[140:143], v[212:215], v[24:27]
	v_mfma_f32_16x16x32_bf16 v[12:15], v[128:131], v[228:231], v[12:15]
	v_mfma_f32_16x16x32_bf16 v[12:15], v[132:135], v[232:235], v[12:15]
	v_mfma_f32_16x16x32_bf16 v[8:11], v[136:139], v[228:231], v[8:11]
	v_mfma_f32_16x16x32_bf16 v[8:11], v[140:143], v[232:235], v[8:11]
	s_setprio 0
	s_setprio 1
	v_mfma_f32_16x16x32_bf16 v[52:55], v[144:147], v[184:187], v[52:55]
	v_mfma_f32_16x16x32_bf16 v[52:55], v[148:151], v[188:191], v[52:55]
	v_mfma_f32_16x16x32_bf16 v[48:51], v[164:167], v[184:187], v[48:51]
	v_mfma_f32_16x16x32_bf16 v[48:51], v[180:183], v[188:191], v[48:51]
	v_mfma_f32_16x16x32_bf16 v[36:39], v[144:147], v[200:203], v[36:39]
	v_mfma_f32_16x16x32_bf16 v[36:39], v[148:151], v[204:207], v[36:39]
	v_mfma_f32_16x16x32_bf16 v[32:35], v[164:167], v[200:203], v[32:35]
	v_mfma_f32_16x16x32_bf16 v[32:35], v[180:183], v[204:207], v[32:35]
	v_mfma_f32_16x16x32_bf16 v[20:23], v[144:147], v[208:211], v[20:23]
	v_mfma_f32_16x16x32_bf16 v[20:23], v[148:151], v[212:215], v[20:23]
	v_mfma_f32_16x16x32_bf16 v[16:19], v[164:167], v[208:211], v[16:19]
	v_mfma_f32_16x16x32_bf16 v[16:19], v[180:183], v[212:215], v[16:19]
	v_mfma_f32_16x16x32_bf16 v[4:7], v[144:147], v[228:231], v[4:7]
	v_mfma_f32_16x16x32_bf16 v[4:7], v[148:151], v[232:235], v[4:7]
	v_mfma_f32_16x16x32_bf16 v[0:3], v[164:167], v[228:231], v[0:3]
	v_mfma_f32_16x16x32_bf16 v[0:3], v[180:183], v[232:235], v[0:3]
	s_setprio 0
	s_barrier
	s_add_i32 s50, s50, 2
	s_add_u32 s0, s0, 0x100
	s_addc_u32 s1, s1, 0
	s_add_u32 s48, s48, 0x100
	s_addc_u32 s49, s49, 0
	s_cmp_gt_u32 s50, 13
	s_cbranch_scc0 .LBB0_890
	s_and_b64 vcc, exec, s[8:9]
	s_cbranch_vccz .LBB0_893
	s_barrier

.LBB0_986:
	s_add_u32 s34, s8, 0xfff00080
	s_addc_u32 s35, s9, -1
	s_add_i32 s36, 0, 0x10000
	s_cmp_eq_u32 s57, 60
	s_cselect_b32 s41, s23, s35
	s_cselect_b32 s40, s53, s34
	s_cselect_b32 s35, s19, s56
	s_cselect_b32 s34, s54, s55
	s_add_i32 s58, 0, 0x14000
	v_add_u32_e32 v140, s36, v228
	v_add_u32_e32 v156, s58, v228
	ds_read_b128 v[128:131], v140
	ds_read_b128 v[132:135], v140 offset:1024
	ds_read_b128 v[136:139], v140 offset:2048
	ds_read_b128 v[140:143], v140 offset:3072
	ds_read_b128 v[144:147], v156
	ds_read_b128 v[148:151], v156 offset:1024
	ds_read_b128 v[152:155], v156 offset:2048
	ds_read_b128 v[156:159], v156 offset:3072
	s_add_i32 m0, s44, 0xc000
	ds_read_b128 v[160:163], v230
	ds_read_b128 v[164:167], v230 offset:1024
	ds_read_b128 v[190:193], v230 offset:2048
	ds_read_b128 v[194:197], v230 offset:3072
	ds_read_b128 v[198:201], v230 offset:4096
	ds_read_b128 v[202:205], v230 offset:5120
	ds_read_b128 v[206:209], v230 offset:6144
	ds_read_b128 v[210:213], v230 offset:7168
	global_load_lds_dwordx4 v186, s[8:9]
	s_add_i32 m0, s44, 0xe000
	s_nop 0
	global_load_lds_dwordx4 v188, s[8:9]
	s_waitcnt vmcnt(8)
	s_waitcnt lgkmcnt(0)
	s_barrier
	s_setprio 1
	s_waitcnt lgkmcnt(0)
	v_mfma_f32_16x16x32_bf16 v[124:127], v[128:131], v[160:163], v[124:127]
	v_mfma_f32_16x16x32_bf16 v[124:127], v[132:135], v[164:167], v[124:127]
	v_mfma_f32_16x16x32_bf16 v[120:123], v[136:139], v[160:163], v[120:123]
	v_mfma_f32_16x16x32_bf16 v[120:123], v[140:143], v[164:167], v[120:123]
	v_mfma_f32_16x16x32_bf16 v[108:111], v[128:131], v[190:193], v[108:111]
	v_mfma_f32_16x16x32_bf16 v[108:111], v[132:135], v[194:197], v[108:111]
	v_mfma_f32_16x16x32_bf16 v[104:107], v[136:139], v[190:193], v[104:107]
	v_mfma_f32_16x16x32_bf16 v[104:107], v[140:143], v[194:197], v[104:107]
	v_mfma_f32_16x16x32_bf16 v[92:95], v[128:131], v[198:201], v[92:95]
	v_mfma_f32_16x16x32_bf16 v[92:95], v[132:135], v[202:205], v[92:95]
	v_mfma_f32_16x16x32_bf16 v[88:91], v[136:139], v[198:201], v[88:91]
	v_mfma_f32_16x16x32_bf16 v[88:91], v[140:143], v[202:205], v[88:91]
	v_mfma_f32_16x16x32_bf16 v[76:79], v[128:131], v[206:209], v[76:79]
	v_mfma_f32_16x16x32_bf16 v[76:79], v[132:135], v[210:213], v[76:79]
	v_mfma_f32_16x16x32_bf16 v[72:75], v[136:139], v[206:209], v[72:75]
	v_mfma_f32_16x16x32_bf16 v[72:75], v[140:143], v[210:213], v[72:75]
	s_setprio 0
	s_setprio 1
	v_mfma_f32_16x16x32_bf16 v[116:119], v[144:147], v[160:163], v[116:119]
	v_mfma_f32_16x16x32_bf16 v[116:119], v[148:151], v[164:167], v[116:119]
	v_mfma_f32_16x16x32_bf16 v[112:115], v[152:155], v[160:163], v[112:115]
	v_mfma_f32_16x16x32_bf16 v[112:115], v[156:159], v[164:167], v[112:115]
	v_mfma_f32_16x16x32_bf16 v[100:103], v[144:147], v[190:193], v[100:103]
	v_mfma_f32_16x16x32_bf16 v[100:103], v[148:151], v[194:197], v[100:103]
	v_mfma_f32_16x16x32_bf16 v[96:99], v[152:155], v[190:193], v[96:99]
	v_mfma_f32_16x16x32_bf16 v[96:99], v[156:159], v[194:197], v[96:99]
	v_mfma_f32_16x16x32_bf16 v[84:87], v[144:147], v[198:201], v[84:87]
	v_mfma_f32_16x16x32_bf16 v[84:87], v[148:151], v[202:205], v[84:87]
	v_mfma_f32_16x16x32_bf16 v[80:83], v[152:155], v[198:201], v[80:83]
	v_mfma_f32_16x16x32_bf16 v[80:83], v[156:159], v[202:205], v[80:83]
	v_mfma_f32_16x16x32_bf16 v[68:71], v[144:147], v[206:209], v[68:71]
	v_mfma_f32_16x16x32_bf16 v[68:71], v[148:151], v[210:213], v[68:71]
	v_mfma_f32_16x16x32_bf16 v[64:67], v[152:155], v[206:209], v[64:67]
	v_mfma_f32_16x16x32_bf16 v[64:67], v[156:159], v[210:213], v[64:67]
	s_setprio 0
	s_barrier
	s_add_i32 s36, s36, s43
	s_add_u32 s98, s34, s20
	s_addc_u32 s99, s35, s21
	s_mov_b32 m0, s36
	ds_read_b128 v[160:163], v230 offset:16384
	ds_read_b128 v[164:167], v230 offset:17408
	ds_read_b128 v[190:193], v230 offset:18432
	ds_read_b128 v[194:197], v230 offset:19456
	ds_read_b128 v[198:201], v230 offset:20480
	ds_read_b128 v[202:205], v230 offset:21504
	ds_read_b128 v[206:209], v230 offset:22528
	ds_read_b128 v[210:213], v230 offset:23552
	global_load_lds_dwordx4 v168, s[34:35]
	s_add_i32 m0, s36, 0x2000
	s_add_u32 s36, s34, 0x100000
	s_addc_u32 s37, s35, 0
	s_add_i32 s58, s58, s43
	global_load_lds_dwordx4 v180, s[34:35]
	s_mov_b32 m0, s58
	s_nop 0
	global_load_lds_dwordx4 v168, s[36:37]
	s_add_i32 m0, s58, 0x2000
	s_nop 0
	global_load_lds_dwordx4 v180, s[36:37]
	s_add_u32 s100, s40, s20
	s_addc_u32 s101, s41, s21
	s_mov_b32 m0, s44
	s_nop 0
	global_load_lds_dwordx4 v184, s[40:41]
	s_mov_b32 m0, s45
	s_nop 0
	global_load_lds_dwordx4 v182, s[40:41]
	s_waitcnt vmcnt(8)
	s_waitcnt lgkmcnt(0)
	s_barrier
	s_setprio 1
	s_waitcnt lgkmcnt(0)
	v_mfma_f32_16x16x32_bf16 v[60:63], v[128:131], v[160:163], v[60:63]
	v_mfma_f32_16x16x32_bf16 v[60:63], v[132:135], v[164:167], v[60:63]
	v_mfma_f32_16x16x32_bf16 v[56:59], v[136:139], v[160:163], v[56:59]
	v_mfma_f32_16x16x32_bf16 v[56:59], v[140:143], v[164:167], v[56:59]
	v_mfma_f32_16x16x32_bf16 v[44:47], v[128:131], v[190:193], v[44:47]
	v_mfma_f32_16x16x32_bf16 v[44:47], v[132:135], v[194:197], v[44:47]
	v_mfma_f32_16x16x32_bf16 v[40:43], v[136:139], v[190:193], v[40:43]
	v_mfma_f32_16x16x32_bf16 v[40:43], v[140:143], v[194:197], v[40:43]
	v_mfma_f32_16x16x32_bf16 v[28:31], v[128:131], v[198:201], v[28:31]
	v_mfma_f32_16x16x32_bf16 v[28:31], v[132:135], v[202:205], v[28:31]
	v_mfma_f32_16x16x32_bf16 v[24:27], v[136:139], v[198:201], v[24:27]
	v_mfma_f32_16x16x32_bf16 v[24:27], v[140:143], v[202:205], v[24:27]
	v_mfma_f32_16x16x32_bf16 v[12:15], v[128:131], v[206:209], v[12:15]
	v_mfma_f32_16x16x32_bf16 v[12:15], v[132:135], v[210:213], v[12:15]
	v_mfma_f32_16x16x32_bf16 v[8:11], v[136:139], v[206:209], v[8:11]
	v_mfma_f32_16x16x32_bf16 v[8:11], v[140:143], v[210:213], v[8:11]
	s_setprio 0
	s_setprio 1
	v_mfma_f32_16x16x32_bf16 v[52:55], v[144:147], v[160:163], v[52:55]
	v_mfma_f32_16x16x32_bf16 v[52:55], v[148:151], v[164:167], v[52:55]
	v_mfma_f32_16x16x32_bf16 v[48:51], v[152:155], v[160:163], v[48:51]
	v_mfma_f32_16x16x32_bf16 v[48:51], v[156:159], v[164:167], v[48:51]
	v_mfma_f32_16x16x32_bf16 v[36:39], v[144:147], v[190:193], v[36:39]
	v_mfma_f32_16x16x32_bf16 v[36:39], v[148:151], v[194:197], v[36:39]
	v_mfma_f32_16x16x32_bf16 v[32:35], v[152:155], v[190:193], v[32:35]
	v_mfma_f32_16x16x32_bf16 v[32:35], v[156:159], v[194:197], v[32:35]
	v_mfma_f32_16x16x32_bf16 v[20:23], v[144:147], v[198:201], v[20:23]
	v_mfma_f32_16x16x32_bf16 v[20:23], v[148:151], v[202:205], v[20:23]
	v_mfma_f32_16x16x32_bf16 v[16:19], v[152:155], v[198:201], v[16:19]
	v_mfma_f32_16x16x32_bf16 v[16:19], v[156:159], v[202:205], v[16:19]
	v_mfma_f32_16x16x32_bf16 v[4:7], v[144:147], v[206:209], v[4:7]
	v_mfma_f32_16x16x32_bf16 v[4:7], v[148:151], v[210:213], v[4:7]
	v_mfma_f32_16x16x32_bf16 v[0:3], v[152:155], v[206:209], v[0:3]
	v_mfma_f32_16x16x32_bf16 v[0:3], v[156:159], v[210:213], v[0:3]
	s_setprio 0
	s_barrier
	s_add_i32 s58, 0, 0x18000
	s_add_i32 s59, 0, 0x1c000
	v_add_u32_e32 v140, s58, v228
	v_add_u32_e32 v156, s59, v228
	ds_read_b128 v[128:131], v140
	ds_read_b128 v[132:135], v140 offset:1024
	ds_read_b128 v[136:139], v140 offset:2048
	ds_read_b128 v[140:143], v140 offset:3072
	ds_read_b128 v[144:147], v156
	ds_read_b128 v[148:151], v156 offset:1024
	ds_read_b128 v[152:155], v156 offset:2048
	ds_read_b128 v[156:159], v156 offset:3072
	s_add_u32 s36, s40, 0x100000
	s_addc_u32 s37, s41, 0
	s_mov_b32 m0, s46
	ds_read_b128 v[160:163], v230 offset:32768
	ds_read_b128 v[164:167], v230 offset:33792
	ds_read_b128 v[190:193], v230 offset:34816
	ds_read_b128 v[194:197], v230 offset:35840
	ds_read_b128 v[198:201], v230 offset:36864
	ds_read_b128 v[202:205], v230 offset:37888
	ds_read_b128 v[206:209], v230 offset:38912
	ds_read_b128 v[210:213], v230 offset:39936
	global_load_lds_dwordx4 v184, s[36:37]
	s_mov_b32 m0, s47
	s_nop 0
	global_load_lds_dwordx4 v182, s[36:37]
	s_waitcnt vmcnt(8)
	s_waitcnt lgkmcnt(0)
	s_barrier
	s_setprio 1
	s_waitcnt lgkmcnt(0)
	v_mfma_f32_16x16x32_bf16 v[124:127], v[128:131], v[160:163], v[124:127]
	v_mfma_f32_16x16x32_bf16 v[124:127], v[132:135], v[164:167], v[124:127]
	v_mfma_f32_16x16x32_bf16 v[120:123], v[136:139], v[160:163], v[120:123]
	v_mfma_f32_16x16x32_bf16 v[120:123], v[140:143], v[164:167], v[120:123]
	v_mfma_f32_16x16x32_bf16 v[108:111], v[128:131], v[190:193], v[108:111]
	v_mfma_f32_16x16x32_bf16 v[108:111], v[132:135], v[194:197], v[108:111]
	v_mfma_f32_16x16x32_bf16 v[104:107], v[136:139], v[190:193], v[104:107]
	v_mfma_f32_16x16x32_bf16 v[104:107], v[140:143], v[194:197], v[104:107]
	v_mfma_f32_16x16x32_bf16 v[92:95], v[128:131], v[198:201], v[92:95]
	v_mfma_f32_16x16x32_bf16 v[92:95], v[132:135], v[202:205], v[92:95]
	v_mfma_f32_16x16x32_bf16 v[88:91], v[136:139], v[198:201], v[88:91]
	v_mfma_f32_16x16x32_bf16 v[88:91], v[140:143], v[202:205], v[88:91]
	v_mfma_f32_16x16x32_bf16 v[76:79], v[128:131], v[206:209], v[76:79]
	v_mfma_f32_16x16x32_bf16 v[76:79], v[132:135], v[210:213], v[76:79]
	v_mfma_f32_16x16x32_bf16 v[72:75], v[136:139], v[206:209], v[72:75]
	v_mfma_f32_16x16x32_bf16 v[72:75], v[140:143], v[210:213], v[72:75]
	s_setprio 0
	s_setprio 1
	v_mfma_f32_16x16x32_bf16 v[116:119], v[144:147], v[160:163], v[116:119]
	v_mfma_f32_16x16x32_bf16 v[116:119], v[148:151], v[164:167], v[116:119]
	v_mfma_f32_16x16x32_bf16 v[112:115], v[152:155], v[160:163], v[112:115]
	v_mfma_f32_16x16x32_bf16 v[112:115], v[156:159], v[164:167], v[112:115]
	v_mfma_f32_16x16x32_bf16 v[100:103], v[144:147], v[190:193], v[100:103]
	v_mfma_f32_16x16x32_bf16 v[100:103], v[148:151], v[194:197], v[100:103]
	v_mfma_f32_16x16x32_bf16 v[96:99], v[152:155], v[190:193], v[96:99]
	v_mfma_f32_16x16x32_bf16 v[96:99], v[156:159], v[194:197], v[96:99]
	v_mfma_f32_16x16x32_bf16 v[84:87], v[144:147], v[198:201], v[84:87]
	v_mfma_f32_16x16x32_bf16 v[84:87], v[148:151], v[202:205], v[84:87]
	v_mfma_f32_16x16x32_bf16 v[80:83], v[152:155], v[198:201], v[80:83]
	v_mfma_f32_16x16x32_bf16 v[80:83], v[156:159], v[202:205], v[80:83]
	v_mfma_f32_16x16x32_bf16 v[68:71], v[144:147], v[206:209], v[68:71]
	v_mfma_f32_16x16x32_bf16 v[68:71], v[148:151], v[210:213], v[68:71]
	v_mfma_f32_16x16x32_bf16 v[64:67], v[152:155], v[206:209], v[64:67]
	v_mfma_f32_16x16x32_bf16 v[64:67], v[156:159], v[210:213], v[64:67]
	s_setprio 0
	s_barrier
	s_add_i32 s36, s58, s43
	s_mov_b32 m0, s36
	ds_read_b128 v[160:163], v230 offset:49152
	ds_read_b128 v[164:167], v230 offset:50176
	ds_read_b128 v[190:193], v230 offset:51200
	ds_read_b128 v[194:197], v230 offset:52224
	ds_read_b128 v[198:201], v230 offset:53248
	ds_read_b128 v[202:205], v230 offset:54272
	ds_read_b128 v[206:209], v230 offset:55296
	ds_read_b128 v[210:213], v230 offset:56320
	global_load_lds_dwordx4 v168, s[98:99]
	s_add_i32 m0, s36, 0x2000
	s_add_u32 s34, s34, 0x100080
	s_addc_u32 s35, s35, 0
	s_add_i32 s36, s59, s43
	global_load_lds_dwordx4 v180, s[98:99]
	s_mov_b32 m0, s36
	s_nop 0
	global_load_lds_dwordx4 v168, s[34:35]
	s_add_i32 m0, s36, 0x2000
	s_nop 0
	global_load_lds_dwordx4 v180, s[34:35]
	s_mov_b32 m0, s50
	s_nop 0
	global_load_lds_dwordx4 v184, s[100:101]
	s_mov_b32 m0, s51
	s_nop 0
	global_load_lds_dwordx4 v182, s[100:101]
	s_waitcnt vmcnt(8)
	s_waitcnt lgkmcnt(0)
	s_barrier
	s_setprio 1
	s_waitcnt lgkmcnt(0)
	v_mfma_f32_16x16x32_bf16 v[60:63], v[128:131], v[160:163], v[60:63]
	v_mfma_f32_16x16x32_bf16 v[60:63], v[132:135], v[164:167], v[60:63]
	v_mfma_f32_16x16x32_bf16 v[56:59], v[136:139], v[160:163], v[56:59]
	v_mfma_f32_16x16x32_bf16 v[56:59], v[140:143], v[164:167], v[56:59]
	v_mfma_f32_16x16x32_bf16 v[44:47], v[128:131], v[190:193], v[44:47]
	v_mfma_f32_16x16x32_bf16 v[44:47], v[132:135], v[194:197], v[44:47]
	v_mfma_f32_16x16x32_bf16 v[40:43], v[136:139], v[190:193], v[40:43]
	v_mfma_f32_16x16x32_bf16 v[40:43], v[140:143], v[194:197], v[40:43]
	v_mfma_f32_16x16x32_bf16 v[28:31], v[128:131], v[198:201], v[28:31]
	v_mfma_f32_16x16x32_bf16 v[28:31], v[132:135], v[202:205], v[28:31]
	v_mfma_f32_16x16x32_bf16 v[24:27], v[136:139], v[198:201], v[24:27]
	v_mfma_f32_16x16x32_bf16 v[24:27], v[140:143], v[202:205], v[24:27]
	v_mfma_f32_16x16x32_bf16 v[12:15], v[128:131], v[206:209], v[12:15]
	v_mfma_f32_16x16x32_bf16 v[12:15], v[132:135], v[210:213], v[12:15]
	v_mfma_f32_16x16x32_bf16 v[8:11], v[136:139], v[206:209], v[8:11]
	v_mfma_f32_16x16x32_bf16 v[8:11], v[140:143], v[210:213], v[8:11]
	s_setprio 0
	s_setprio 1
	v_mfma_f32_16x16x32_bf16 v[52:55], v[144:147], v[160:163], v[52:55]
	v_mfma_f32_16x16x32_bf16 v[52:55], v[148:151], v[164:167], v[52:55]
	v_mfma_f32_16x16x32_bf16 v[48:51], v[152:155], v[160:163], v[48:51]
	v_mfma_f32_16x16x32_bf16 v[48:51], v[156:159], v[164:167], v[48:51]
	v_mfma_f32_16x16x32_bf16 v[36:39], v[144:147], v[190:193], v[36:39]
	v_mfma_f32_16x16x32_bf16 v[36:39], v[148:151], v[194:197], v[36:39]
	v_mfma_f32_16x16x32_bf16 v[32:35], v[152:155], v[190:193], v[32:35]
	v_mfma_f32_16x16x32_bf16 v[32:35], v[156:159], v[194:197], v[32:35]
	v_mfma_f32_16x16x32_bf16 v[20:23], v[144:147], v[198:201], v[20:23]
	v_mfma_f32_16x16x32_bf16 v[20:23], v[148:151], v[202:205], v[20:23]
	v_mfma_f32_16x16x32_bf16 v[16:19], v[152:155], v[198:201], v[16:19]
	v_mfma_f32_16x16x32_bf16 v[16:19], v[156:159], v[202:205], v[16:19]
	v_mfma_f32_16x16x32_bf16 v[4:7], v[144:147], v[206:209], v[4:7]
	v_mfma_f32_16x16x32_bf16 v[4:7], v[148:151], v[210:213], v[4:7]
	v_mfma_f32_16x16x32_bf16 v[0:3], v[152:155], v[206:209], v[0:3]
	v_mfma_f32_16x16x32_bf16 v[0:3], v[156:159], v[210:213], v[0:3]
	s_setprio 0
	s_barrier
	s_add_i32 s57, s57, 2
	s_add_u32 s8, s8, 0x100
	s_addc_u32 s9, s9, 0
	s_add_u32 s55, s55, 0x100
	s_addc_u32 s56, s56, 0
	s_cmp_gt_u32 s57, 61
	s_cbranch_scc0 .LBB0_986
	s_and_b64 vcc, exec, s[12:13]
	s_cbranch_vccz .LBB0_989
	s_barrier

	.amdhsa_kernel _Z9trunk_fwd4Args
		.amdhsa_group_segment_fixed_size 0
		.amdhsa_private_segment_fixed_size 0
		.amdhsa_kernarg_size 464
		.amdhsa_user_sgpr_count 2
		.amdhsa_user_sgpr_dispatch_ptr 0
		.amdhsa_user_sgpr_queue_ptr 0
		.amdhsa_user_sgpr_kernarg_segment_ptr 1
		.amdhsa_user_sgpr_dispatch_id 0
		.amdhsa_user_sgpr_kernarg_preload_length 0
		.amdhsa_user_sgpr_kernarg_preload_offset 0
		.amdhsa_user_sgpr_private_segment_size 0
		.amdhsa_uses_dynamic_stack 0
		.amdhsa_enable_private_segment 0
		.amdhsa_system_sgpr_workgroup_id_x 1
		.amdhsa_system_sgpr_workgroup_id_y 0
		.amdhsa_system_sgpr_workgroup_id_z 0
		.amdhsa_system_sgpr_workgroup_info 0
		.amdhsa_system_vgpr_workitem_id 2
		.amdhsa_next_free_vgpr 251
		.amdhsa_next_free_sgpr 102
		.amdhsa_accum_offset 252
		.amdhsa_reserve_vcc 1
		.amdhsa_float_round_mode_32 0
		.amdhsa_float_round_mode_16_64 0
		.amdhsa_float_denorm_mode_32 3
		.amdhsa_float_denorm_mode_16_64 3
		.amdhsa_dx10_clamp 1
		.amdhsa_ieee_mode 1
		.amdhsa_fp16_overflow 0
		.amdhsa_tg_split 0
		.amdhsa_exception_fp_ieee_invalid_op 0
		.amdhsa_exception_fp_denorm_src 0
		.amdhsa_exception_fp_ieee_div_zero 0
		.amdhsa_exception_fp_ieee_overflow 0
		.amdhsa_exception_fp_ieee_underflow 0
		.amdhsa_exception_fp_ieee_inexact 0
		.amdhsa_exception_int_div_zero 0
	.end_amdhsa_kernel

amdhsa.kernels:
  - .agpr_count:     0
    .args:
      - .offset:         0
        .size:           208
        .value_kind:     by_value
      - .offset:         208
        .size:           4
        .value_kind:     hidden_block_count_x
      - .offset:         212
        .size:           4
        .value_kind:     hidden_block_count_y
      - .offset:         216
        .size:           4
        .value_kind:     hidden_block_count_z
      - .offset:         220
        .size:           2
        .value_kind:     hidden_group_size_x
      - .offset:         222
        .size:           2
        .value_kind:     hidden_group_size_y
      - .offset:         224
        .size:           2
        .value_kind:     hidden_group_size_z
      - .offset:         226
        .size:           2
        .value_kind:     hidden_remainder_x
      - .offset:         228
        .size:           2
        .value_kind:     hidden_remainder_y
      - .offset:         230
        .size:           2
        .value_kind:     hidden_remainder_z
      - .offset:         248
        .size:           8
        .value_kind:     hidden_global_offset_x
      - .offset:         256
        .size:           8
        .value_kind:     hidden_global_offset_y
      - .offset:         264
        .size:           8
        .value_kind:     hidden_global_offset_z
      - .offset:         272
        .size:           2
        .value_kind:     hidden_grid_dims
      - .offset:         296
        .size:           8
        .value_kind:     hidden_multigrid_sync_arg
      - .offset:         328
        .size:           4
        .value_kind:     hidden_dynamic_lds_size
    .group_segment_fixed_size: 0
    .kernarg_segment_align: 8
    .kernarg_segment_size: 464
    .language:       OpenCL C
    .language_version:
      - 2
      - 0
    .max_flat_workgroup_size: 512
    .name:           _Z9trunk_fwd4Args
    .private_segment_fixed_size: 0
    .sgpr_count:     108
    .sgpr_spill_count: 324
    .symbol:         _Z9trunk_fwd4Args.kd
    .uniform_work_group_size: 1
    .uses_dynamic_stack: false
    .vgpr_count:     251
    .vgpr_spill_count: 0
    .wavefront_size: 64
